# window: QK starts after the 8 K-fragment LDS reads (V waited before first PV MFMA); plus previous
# baseline (speedup 1.0000x reference)
.Lwin_nodma:
	s_cmp_lt_i32 s12, s22
	s_cbranch_scc1 .Lwin_skip
	s_cmp_gt_i32 s12, s24
	s_cbranch_scc1 .Lwin_skip
	v_add_u32_e32 v61, s36, v60
	ds_read_b128 v[120:123], v61
	ds_read_b128 v[116:119], v61 offset:1024
	ds_read_b128 v[112:115], v61 offset:2048
	ds_read_b128 v[108:111], v61 offset:3072
	ds_read_b128 v[104:107], v61 offset:4096
	ds_read_b128 v[100:103], v61 offset:5120
	ds_read_b128 v[96:99], v61 offset:6144
	ds_read_b128 v[92:95], v61 offset:7168
	ds_read_b128 v[56:59], v61 offset:8192
	ds_read_b128 v[52:55], v61 offset:9216
	ds_read_b128 v[48:51], v61 offset:10240
	ds_read_b128 v[40:43], v61 offset:11264
	ds_read_b128 v[36:39], v61 offset:12288
	ds_read_b128 v[32:35], v61 offset:13312
	ds_read_b128 v[28:31], v61 offset:14336
	ds_read_b128 v[24:27], v61 offset:15360
	s_lshl_b32 s93, s12, 6
	v_mov_b32_e32 v230, s93
	v_add_u32_e32 v230, 0x7f, v230
	s_add_i32 s99, s93, 63
	s_waitcnt lgkmcnt(8)
	s_cmp_ge_i32 s93, s98
	s_cbranch_scc0 .Lwin_msk
	s_cmp_le_i32 s99, s32
	s_cbranch_scc0 .Lwin_msk
	v_mfma_f32_16x16x32_bf16 v[120:123], v[120:123], v[16:19], 0
	v_mfma_f32_16x16x32_bf16 v[112:115], v[112:115], v[16:19], 0
	v_mfma_f32_16x16x32_bf16 v[116:119], v[116:119], v[12:15], v[120:123]
	v_mfma_f32_16x16x32_bf16 v[104:107], v[104:107], v[16:19], 0
	v_mfma_f32_16x16x32_bf16 v[108:111], v[108:111], v[12:15], v[112:115]
	s_nop 5
	v_max_f32_e32 v1, v116, v117
	v_mfma_f32_16x16x32_bf16 v[96:99], v[96:99], v[16:19], 0
	v_max_f32_e32 v2, v118, v119
	v_mfma_f32_16x16x32_bf16 v[100:103], v[100:103], v[12:15], v[104:107]
	v_max_f32_e32 v3, v110, v111
	v_mfma_f32_16x16x32_bf16 v[92:95], v[92:95], v[12:15], v[96:99]
	v_max3_f32 v3, v108, v109, v3
	v_max3_f32 v1, v1, v2, v3
	s_nop 1
	s_nop 1
	v_max_f32_e32 v2, v102, v103
	s_nop 0
	v_max_f32_e32 v3, v94, v95
	v_max3_f32 v2, v100, v101, v2
	v_max3_f32 v3, v92, v93, v3
	v_max3_f32 v1, v1, v2, v3
	v_mov_b32_e32 v2, v1
	s_nop 1
	v_permlane16_swap_b32_e32 v1, v2
	v_max_f32_e32 v1, v1, v2
	v_mov_b32_e32 v2, v1
	s_nop 1
	v_permlane32_swap_b32_e32 v1, v2
	v_max3_f32 v1, v235, v1, v2
	v_sub_f32_e32 v3, v116, v1
	v_exp_f32_e32 v3, v3
	v_sub_f32_e32 v96, v117, v1
	v_exp_f32_e32 v96, v96
	v_sub_f32_e32 v97, v118, v1
	v_exp_f32_e32 v97, v97
	v_sub_f32_e32 v98, v119, v1
	v_exp_f32_e32 v98, v98
	v_sub_f32_e32 v104, v108, v1
	v_add_f32_e32 v99, 0, v3
	v_exp_f32_e32 v104, v104
	v_sub_f32_e32 v105, v109, v1
	v_add_f32_e32 v99, v96, v99
	v_exp_f32_e32 v105, v105
	v_sub_f32_e32 v106, v110, v1
	v_add_f32_e32 v99, v97, v99
	v_exp_f32_e32 v106, v106
	v_sub_f32_e32 v107, v111, v1
	v_add_f32_e32 v99, v98, v99
	v_exp_f32_e32 v107, v107
	v_add_f32_e32 v99, v104, v99
	v_sub_f32_e32 v2, v235, v1
	v_add_f32_e32 v99, v105, v99
	v_sub_f32_e32 v92, v92, v1
	v_add_f32_e32 v99, v106, v99
	v_exp_f32_e32 v109, v92
	v_exp_f32_e32 v92, v2
	v_sub_f32_e32 v2, v93, v1
	v_add_f32_e32 v108, v107, v99
	v_sub_f32_e32 v99, v100, v1
	v_exp_f32_e32 v93, v2
	v_exp_f32_e32 v100, v99
	v_sub_f32_e32 v99, v101, v1
	v_exp_f32_e32 v101, v99
	v_sub_f32_e32 v99, v102, v1
	v_exp_f32_e32 v102, v99
	v_sub_f32_e32 v99, v103, v1
	v_exp_f32_e32 v103, v99
	v_cvt_pk_bf16_f32 v96, v3, v96
	v_cvt_pk_bf16_f32 v97, v97, v98
	v_cvt_pk_bf16_f32 v98, v104, v105
	v_cvt_pk_bf16_f32 v99, v106, v107
	v_pk_mul_f32 v[22:23], v[22:23], v[92:93] op_sel_hi:[1,0]
	v_pk_mul_f32 v[20:21], v[20:21], v[92:93] op_sel_hi:[1,0]
	v_sub_f32_e32 v2, v94, v1
	v_pk_mul_f32 v[46:47], v[46:47], v[92:93] op_sel_hi:[1,0]
	v_pk_mul_f32 v[44:45], v[44:45], v[92:93] op_sel_hi:[1,0]
	s_waitcnt lgkmcnt(0)
	v_mfma_f32_16x16x32_bf16 v[20:23], v[52:55], v[96:99], v[20:23]
	v_sub_f32_e32 v52, v95, v1
	v_pk_mul_f32 v[6:7], v[6:7], v[92:93] op_sel_hi:[1,0]
	v_pk_mul_f32 v[4:5], v[4:5], v[92:93] op_sel_hi:[1,0]
	v_mfma_f32_16x16x32_bf16 v[44:47], v[56:59], v[96:99], v[44:47]
	v_exp_f32_e32 v56, v2
	v_pk_mul_f32 v[10:11], v[10:11], v[92:93] op_sel_hi:[1,0]
	v_pk_mul_f32 v[8:9], v[8:9], v[92:93] op_sel_hi:[1,0]
	v_mfma_f32_16x16x32_bf16 v[2:5], v[48:51], v[96:99], v[4:7]
	v_exp_f32_e32 v48, v52
	v_mov_b32_e32 v235, v1
	v_mfma_f32_16x16x32_bf16 v[8:11], v[40:43], v[96:99], v[8:11]
	v_add_f32_e32 v6, v100, v108
	v_add_f32_e32 v6, v101, v6
	v_add_f32_e32 v6, v102, v6
	v_add_f32_e32 v6, v103, v6
	v_cvt_pk_bf16_f32 v40, v100, v101
	v_cvt_pk_bf16_f32 v41, v102, v103
	v_cvt_pk_bf16_f32 v42, v109, v93
	v_cvt_pk_bf16_f32 v43, v56, v48
	v_add_f32_e32 v6, v109, v6
	s_nop 0
	v_mfma_f32_16x16x32_bf16 v[44:47], v[36:39], v[40:43], v[44:47]
	v_mfma_f32_16x16x32_bf16 v[20:23], v[32:35], v[40:43], v[20:23]
	v_add_f32_e32 v32, v93, v6
	v_mfma_f32_16x16x32_bf16 v[4:7], v[28:31], v[40:43], v[2:5]
	v_mfma_f32_16x16x32_bf16 v[8:11], v[24:27], v[40:43], v[8:11]
	s_nop 1
	v_add_f32_e32 v2, v56, v32
	v_add_f32_e32 v234, v48, v2
	v_fmac_f32_e32 v234, v236, v92
	s_branch .Lwin_join
.Lwin_msk:
	v_mfma_f32_16x16x32_bf16 v[120:123], v[120:123], v[16:19], 0
	v_add_u32_e32 v1, v212, v230
	v_add_u32_e32 v2, 0xffffff81, v1
	v_cmp_lt_i32_e32 vcc, v2, v232
	v_mfma_f32_16x16x32_bf16 v[116:119], v[116:119], v[12:15], v[120:123]
	v_cmp_gt_i32_e64 s[0:1], v2, v228
	s_or_b64 vcc, vcc, s[0:1]
	v_cmp_ge_i32_e64 s[0:1], v2, v228
	v_mfma_f32_16x16x32_bf16 v[112:115], v[112:115], v[16:19], 0
	v_mfma_f32_16x16x32_bf16 v[104:107], v[104:107], v[16:19], 0
	s_nop 2
	v_cndmask_b32_e32 v3, v116, v220, vcc
	v_add_u32_e32 v116, 0xffffff82, v1
	v_cmp_lt_i32_e32 vcc, v116, v232
	v_mfma_f32_16x16x32_bf16 v[108:111], v[108:111], v[12:15], v[112:115]
	s_or_b64 vcc, s[0:1], vcc
	v_cndmask_b32_e32 v2, v117, v220, vcc
	s_nop 0
	v_add_u32_e32 v112, 0xffffff83, v1
	v_cmp_lt_i32_e32 vcc, v112, v232
	v_cmp_gt_i32_e64 s[0:1], v112, v228
	s_or_b64 vcc, vcc, s[0:1]
	v_mfma_f32_16x16x32_bf16 v[100:103], v[100:103], v[12:15], v[104:107]
	v_cndmask_b32_e32 v112, v118, v220, vcc
	s_nop 1
	v_add_u32_e32 v104, 0xffffff84, v1
	v_mfma_f32_16x16x32_bf16 v[96:99], v[96:99], v[16:19], 0
	v_cmp_lt_i32_e32 vcc, v104, v232
	v_cmp_gt_i32_e64 s[0:1], v104, v228
	s_or_b64 vcc, vcc, s[0:1]
	v_add_u32_e32 v105, 0xffffff91, v1
	v_cndmask_b32_e32 v104, v119, v220, vcc
	v_cmp_lt_i32_e32 vcc, v105, v232
	v_cmp_gt_i32_e64 s[0:1], v105, v228
	v_mfma_f32_16x16x32_bf16 v[92:95], v[92:95], v[12:15], v[96:99]
	s_or_b64 vcc, vcc, s[0:1]
	v_add_u32_e32 v105, 0xffffffa1, v1
	s_nop 0
	v_add_u32_e32 v97, 0xffffff92, v1
	v_cndmask_b32_e32 v96, v108, v220, vcc
	v_cmp_lt_i32_e32 vcc, v97, v232
	v_cmp_gt_i32_e64 s[0:1], v97, v228
	s_or_b64 vcc, vcc, s[0:1]
	v_add_u32_e32 v98, 0xffffff93, v1
	v_cndmask_b32_e32 v97, v109, v220, vcc
	v_cmp_lt_i32_e32 vcc, v98, v232
	v_cmp_gt_i32_e64 s[0:1], v98, v228
	s_or_b64 vcc, vcc, s[0:1]
	v_add_u32_e32 v99, 0xffffff94, v1
	v_cndmask_b32_e32 v98, v110, v220, vcc
	v_cmp_lt_i32_e32 vcc, v99, v232
	v_cmp_gt_i32_e64 s[0:1], v99, v228
	s_or_b64 vcc, vcc, s[0:1]
	v_cndmask_b32_e32 v99, v111, v220, vcc
	v_cmp_lt_i32_e32 vcc, v105, v232
	v_cmp_gt_i32_e64 s[0:1], v105, v228
	s_or_b64 vcc, vcc, s[0:1]
	v_add_u32_e32 v105, 0xffffffa2, v1
	v_cndmask_b32_e32 v100, v100, v220, vcc
	v_cmp_lt_i32_e32 vcc, v105, v232
	v_cmp_gt_i32_e64 s[0:1], v105, v228
	s_or_b64 vcc, vcc, s[0:1]
	v_add_u32_e32 v105, 0xffffffa3, v1
	v_cndmask_b32_e32 v101, v101, v220, vcc
	v_cmp_lt_i32_e32 vcc, v105, v232
	v_cmp_gt_i32_e64 s[0:1], v105, v228
	s_or_b64 vcc, vcc, s[0:1]
	v_add_u32_e32 v105, 0xffffffa4, v1
	v_cndmask_b32_e32 v102, v102, v220, vcc
	v_cmp_lt_i32_e32 vcc, v105, v232
	v_cmp_gt_i32_e64 s[0:1], v105, v228
	s_or_b64 vcc, vcc, s[0:1]
	v_add_u32_e32 v105, 0xffffffb1, v1
	v_cndmask_b32_e32 v103, v103, v220, vcc
	v_cmp_lt_i32_e32 vcc, v105, v232
	v_cmp_gt_i32_e64 s[0:1], v105, v228
	s_or_b64 vcc, vcc, s[0:1]
	v_add_u32_e32 v105, 0xffffffb2, v1
	v_cndmask_b32_e32 v92, v92, v220, vcc
	v_cmp_lt_i32_e32 vcc, v105, v232
	v_cmp_gt_i32_e64 s[0:1], v105, v228
	s_or_b64 vcc, vcc, s[0:1]
	v_add_u32_e32 v105, 0xffffffb3, v1
	v_cndmask_b32_e32 v93, v93, v220, vcc
	v_cmp_lt_i32_e32 vcc, v105, v232
	v_cmp_gt_i32_e64 s[0:1], v105, v228
	s_or_b64 vcc, vcc, s[0:1]
	v_add_u32_e32 v1, 0xffffffb4, v1
	v_cndmask_b32_e32 v94, v94, v220, vcc
	v_cmp_lt_i32_e32 vcc, v1, v232
	v_cmp_gt_i32_e64 s[0:1], v1, v228
	s_or_b64 vcc, vcc, s[0:1]
	v_cndmask_b32_e32 v1, v95, v220, vcc
	v_max_f32_e32 v95, v3, v2
	v_max_f32_e32 v105, v112, v104
	v_max_f32_e32 v106, v98, v99
	v_max3_f32 v106, v96, v97, v106
	v_max3_f32 v95, v95, v105, v106
	v_max_f32_e32 v105, v102, v103
	v_max_f32_e32 v106, v94, v1
	v_max3_f32 v105, v100, v101, v105
	v_max3_f32 v106, v92, v93, v106
	v_max3_f32 v95, v95, v105, v106
	v_mov_b32_e32 v105, v95
	v_cmp_lt_f32_e32 vcc, s83, v3
	s_nop 1
	v_permlane16_swap_b32_e32 v95, v105
	v_max_f32_e32 v95, v95, v105
	v_mov_b32_e32 v105, v95
	s_nop 1
	v_permlane32_swap_b32_e32 v95, v105
	v_max3_f32 v105, v235, v95, v105
	v_sub_f32_e32 v95, v3, v105
	v_exp_f32_e32 v95, v95
	v_sub_f32_e32 v107, v2, v105
	v_exp_f32_e32 v107, v107
	v_sub_f32_e32 v108, v112, v105
	v_exp_f32_e32 v108, v108
	v_cndmask_b32_e32 v3, 0, v95, vcc
	v_cmp_lt_f32_e32 vcc, s83, v2
	v_sub_f32_e32 v109, v96, v105
	v_exp_f32_e32 v109, v109
	v_cndmask_b32_e32 v2, 0, v107, vcc
	v_cmp_lt_f32_e32 vcc, s83, v112
	v_add_f32_e32 v95, 0, v3
	v_add_f32_e32 v95, v2, v95
	v_cndmask_b32_e32 v107, 0, v108, vcc
	v_sub_f32_e32 v108, v104, v105
	v_exp_f32_e32 v108, v108
	v_cmp_lt_f32_e32 vcc, s83, v104
	v_add_f32_e32 v95, v107, v95
	v_sub_f32_e32 v106, v235, v105
	v_cndmask_b32_e32 v104, 0, v108, vcc
	v_cmp_lt_f32_e32 vcc, s83, v96
	v_sub_f32_e32 v96, v97, v105
	v_exp_f32_e32 v96, v96
	v_cndmask_b32_e32 v108, 0, v109, vcc
	v_sub_f32_e32 v109, v98, v105
	v_cmp_lt_f32_e32 vcc, s83, v97
	v_exp_f32_e32 v109, v109
	v_add_f32_e32 v95, v104, v95
	v_cndmask_b32_e32 v97, 0, v96, vcc
	v_sub_f32_e32 v96, v99, v105
	v_exp_f32_e32 v96, v96
	v_add_f32_e32 v95, v108, v95
	v_cmp_lt_f32_e32 vcc, s83, v98
	v_add_f32_e32 v95, v97, v95
	v_mov_b32_e32 v235, v105
	v_cndmask_b32_e32 v98, 0, v109, vcc
	v_cmp_lt_f32_e32 vcc, s83, v99
	v_add_f32_e32 v95, v98, v95
	v_sub_f32_e32 v109, v100, v105
	v_cndmask_b32_e32 v99, 0, v96, vcc
	v_exp_f32_e32 v109, v109
	v_add_f32_e32 v110, v99, v95
	v_sub_f32_e32 v95, v101, v105
	v_exp_f32_e32 v95, v95
	v_sub_f32_e32 v96, v102, v105
	v_cmp_lt_f32_e32 vcc, s83, v100
	v_exp_f32_e32 v96, v96
	s_nop 0
	v_cndmask_b32_e32 v100, 0, v109, vcc
	v_cmp_lt_f32_e32 vcc, s83, v101
	s_nop 1
	v_cndmask_b32_e32 v101, 0, v95, vcc
	v_sub_f32_e32 v95, v103, v105
	v_cmp_lt_f32_e32 vcc, s83, v102
	v_exp_f32_e32 v95, v95
	s_nop 0
	v_cndmask_b32_e32 v102, 0, v96, vcc
	v_sub_f32_e32 v96, v92, v105
	v_exp_f32_e32 v96, v96
	v_cmp_lt_f32_e32 vcc, s83, v103
	s_nop 1
	v_cndmask_b32_e32 v103, 0, v95, vcc
	v_cmp_lt_f32_e32 vcc, s83, v92
	v_sub_f32_e32 v92, v93, v105
	v_exp_f32_e32 v92, v92
	v_sub_f32_e32 v95, v94, v105
	v_cndmask_b32_e32 v109, 0, v96, vcc
	v_exp_f32_e32 v95, v95
	v_exp_f32_e32 v96, v106
	v_cmp_lt_f32_e32 vcc, s83, v93
	v_cvt_pk_bf16_f32 v93, v107, v104
	v_pk_mul_f32 v[22:23], v[22:23], v[96:97] op_sel_hi:[1,0]
	v_cndmask_b32_e32 v106, 0, v92, vcc
	v_cmp_lt_f32_e32 vcc, s83, v94
	v_cvt_pk_bf16_f32 v92, v3, v2
	v_cvt_pk_bf16_f32 v94, v108, v97
	v_cndmask_b32_e32 v111, 0, v95, vcc
	v_cvt_pk_bf16_f32 v95, v98, v99
	v_sub_f32_e32 v2, v1, v105
	v_pk_mul_f32 v[20:21], v[20:21], v[96:97] op_sel_hi:[1,0]
	v_pk_mul_f32 v[6:7], v[6:7], v[96:97] op_sel_hi:[1,0]
	v_pk_mul_f32 v[4:5], v[4:5], v[96:97] op_sel_hi:[1,0]
	s_waitcnt lgkmcnt(0)
	v_mfma_f32_16x16x32_bf16 v[20:23], v[52:55], v[92:95], v[20:23]
	v_exp_f32_e32 v52, v2
	v_pk_mul_f32 v[46:47], v[46:47], v[96:97] op_sel_hi:[1,0]
	v_pk_mul_f32 v[44:45], v[44:45], v[96:97] op_sel_hi:[1,0]
	v_mfma_f32_16x16x32_bf16 v[2:5], v[48:51], v[92:95], v[4:7]
	v_mul_f32_e64 v10, v10, v96
	v_mul_f32_e64 v11, v11, v96
	v_pk_mul_f32 v[8:9], v[8:9], v[96:97] op_sel_hi:[1,0]
	v_cmp_lt_f32_e32 vcc, s83, v1
	v_add_f32_e32 v6, v100, v110
	v_mfma_f32_16x16x32_bf16 v[44:47], v[56:59], v[92:95], v[44:47]
	v_add_f32_e32 v6, v101, v6
	v_add_f32_e32 v6, v102, v6
	v_cndmask_b32_e32 v1, 0, v52, vcc
	v_mfma_f32_16x16x32_bf16 v[8:11], v[40:43], v[92:95], v[8:11]
	v_add_f32_e32 v6, v103, v6
	v_cvt_pk_bf16_f32 v40, v100, v101
	v_cvt_pk_bf16_f32 v41, v102, v103
	v_cvt_pk_bf16_f32 v42, v109, v106
	v_cvt_pk_bf16_f32 v43, v111, v1
	v_add_f32_e32 v6, v109, v6
	s_nop 0
	v_mfma_f32_16x16x32_bf16 v[44:47], v[36:39], v[40:43], v[44:47]
	v_mfma_f32_16x16x32_bf16 v[20:23], v[32:35], v[40:43], v[20:23]
	v_add_f32_e32 v32, v106, v6
	v_mfma_f32_16x16x32_bf16 v[4:7], v[28:31], v[40:43], v[2:5]
	v_mfma_f32_16x16x32_bf16 v[8:11], v[24:27], v[40:43], v[8:11]
	s_nop 1
	v_add_f32_e32 v2, v111, v32
	v_add_f32_e32 v234, v1, v2
	v_fmac_f32_e32 v234, v236, v96
